# GLA loop runs the decay-row LDS write one stage earlier (two barriers fewer per chunk than baseline); Nyquist row loads batched; token-shift coefficients kept in registers
# baseline (speedup 1.0000x reference)
; #define LAS __attribute__((address_space(3)))
; __device__ __forceinline__ unsigned cvt_pk_bf16(float lo, float hi) { const f32x2_t v = {lo, hi}; const bf16x2_t b = __builtin_convertvector(v, bf16x2_t); return __builtin_bit_cast(unsigned, b); }
; __device__ void rwkv_chunk_phase(const Params& p, int l, LAS unsigned char* lds) {
;     ...
;             for (int hf = 0; hf < 2; ++hf) { float fc[8], fp[8], fn[8]; unpack8(rc[hf], fc); unpack8(rp[hf], fp); unpack8(rn[hf], fn);
;                 const f32x4 m0 = *(const LAS f32x4*)(mu_s + cg * 16 + hf * 8), m1 = *(const LAS f32x4*)(mu_s + cg * 16 + hf * 8 + 4);
;                 f32x4 x0, x1;
; #pragma unroll
;                 for (int j = 0; j < 4; ++j) { x0[j] = fc[j] + m0[j] * (0.5f * (fp[j] + fn[j]) - fc[j]); x1[j] = fc[4 + j] + m1[j] * (0.5f * (fp[4 + j] + fn[4 + j]) - fc[4 + j]); }
;                 *(LAS f32x4*)(sh_s + tok * 256 + cg * 16 + hf * 8) = x0; *(LAS f32x4*)(sh_s + tok * 256 + cg * 16 + hf * 8 + 4) = x1; }
;             LBAR();
;             {   const int rt = wid >> 2, ct = wid & 3, row = rt * 16 + r16;
;                 const f32x4 d0 = *(const LAS f32x4*)(sh_s + row * 256 + 192 + quad * 8), d1 = *(const LAS f32x4*)(sh_s + row * 256 + 196 + quad * 8);
;                 const f32x4 e0 = *(const LAS f32x4*)(sh_s + row * 256 + 224 + quad * 8), e1 = *(const LAS f32x4*)(sh_s + row * 256 + 228 + quad * 8);
;                 u32x4 aw, aa;
;                 aw.x = cvt_pk_bf16(tanh_(d0[0]), tanh_(d0[1])); aw.y = cvt_pk_bf16(tanh_(d0[2]), tanh_(d0[3])); aw.z = cvt_pk_bf16(tanh_(d1[0]), tanh_(d1[1])); aw.w = cvt_pk_bf16(tanh_(d1[2]), tanh_(d1[3]));
;                 aa.x = cvt_pk_bf16(e0[0], e0[1]); aa.y = cvt_pk_bf16(e0[2], e0[3]); aa.z = cvt_pk_bf16(e1[0], e1[1]); aa.w = cvt_pk_bf16(e1[2], e1[3]);
;                 const bf16x8 bw = *(const LAS bf16x8*)(w2T + (ct * 16 + r16) * 40 + quad * 8), ba = *(const LAS bf16x8*)(a2T + (ct * 16 + r16) * 40 + quad * 8);
;                 const f32x4 z4 = {0.f, 0.f, 0.f, 0.f};
;                 const f32x4 cw = __builtin_amdgcn_mfma_f32_16x16x32_bf16(__builtin_bit_cast(bf16x8, aw), bw, z4, 0, 0, 0);
;                 const f32x4 ca = __builtin_amdgcn_mfma_f32_16x16x32_bf16(__builtin_bit_cast(bf16x8, aa), ba, z4, 0, 0, 0);
;                 const int col = ct * 16 + r16; const float w0c = c_s[col], a0c = c_s[64 + col];
.LBB0_321:
	s_waitcnt lgkmcnt(0)
	s_barrier
	ds_read_b128 v[230:233], v206 offset:17664
	ds_read_b128 v[234:237], v206 offset:17680
	ds_read_b128 v[238:241], v206 offset:17696
	ds_read_b128 v[242:245], v206 offset:17712
	s_waitcnt lgkmcnt(0)
.Lrw_top:
	s_waitcnt vmcnt(1) lgkmcnt(0)
	v_lshlrev_b32_e32 v40, 16, v16
	v_and_b32_e32 v41, 0xffff0000, v16
	v_lshlrev_b32_e32 v42, 16, v24
	v_and_b32_e32 v43, 0xffff0000, v24
	v_lshlrev_b32_e32 v2, 16, v8
	v_and_b32_e32 v3, 0xffff0000, v8
	v_pk_add_f32 v[40:41], v[40:41], v[42:43]
	v_lshlrev_b32_e32 v42, 16, v26
	v_pk_fma_f32 v[40:41], v[40:41], 0.5, v[2:3] op_sel_hi:[1,0,1] neg_lo:[0,0,1] neg_hi:[0,0,1]
	v_and_b32_e32 v43, 0xffff0000, v26
	v_pk_fma_f32 v[32:33], v[40:41], v[230:231], v[2:3]
	v_lshlrev_b32_e32 v40, 16, v18
	v_and_b32_e32 v41, 0xffff0000, v18
	v_lshlrev_b32_e32 v2, 16, v10
	v_and_b32_e32 v3, 0xffff0000, v10
	v_pk_add_f32 v[40:41], v[40:41], v[42:43]
	v_lshlrev_b32_e32 v42, 16, v25
	v_pk_fma_f32 v[40:41], v[40:41], 0.5, v[2:3] op_sel_hi:[1,0,1] neg_lo:[0,0,1] neg_hi:[0,0,1]
	v_and_b32_e32 v43, 0xffff0000, v25
	v_pk_fma_f32 v[36:37], v[40:41], v[234:235], v[2:3]
	v_lshlrev_b32_e32 v40, 16, v17
	v_and_b32_e32 v41, 0xffff0000, v17
	v_lshlrev_b32_e32 v2, 16, v9
	v_and_b32_e32 v3, 0xffff0000, v9
	v_pk_add_f32 v[40:41], v[40:41], v[42:43]
	v_lshlrev_b32_e32 v42, 16, v27
	v_pk_fma_f32 v[40:41], v[40:41], 0.5, v[2:3] op_sel_hi:[1,0,1] neg_lo:[0,0,1] neg_hi:[0,0,1]
	v_and_b32_e32 v43, 0xffff0000, v27
	v_pk_fma_f32 v[34:35], v[40:41], v[232:233], v[2:3]
	v_lshlrev_b32_e32 v40, 16, v19
	v_and_b32_e32 v41, 0xffff0000, v19
	v_lshlrev_b32_e32 v2, 16, v11
	v_and_b32_e32 v3, 0xffff0000, v11
	v_pk_add_f32 v[40:41], v[40:41], v[42:43]
	v_lshlrev_b32_e32 v42, 16, v28
	v_pk_fma_f32 v[40:41], v[40:41], 0.5, v[2:3] op_sel_hi:[1,0,1] neg_lo:[0,0,1] neg_hi:[0,0,1]
	v_and_b32_e32 v43, 0xffff0000, v28
	v_pk_fma_f32 v[38:39], v[40:41], v[236:237], v[2:3]
	ds_write_b128 v87, v[32:35]
	ds_write_b128 v87, v[36:39] offset:16
	v_lshlrev_b32_e32 v40, 16, v20
	v_and_b32_e32 v41, 0xffff0000, v20
	v_lshlrev_b32_e32 v2, 16, v12
	v_and_b32_e32 v3, 0xffff0000, v12
	v_pk_add_f32 v[40:41], v[40:41], v[42:43]
	v_lshlrev_b32_e32 v42, 16, v30
	v_pk_fma_f32 v[40:41], v[40:41], 0.5, v[2:3] op_sel_hi:[1,0,1] neg_lo:[0,0,1] neg_hi:[0,0,1]
	v_and_b32_e32 v43, 0xffff0000, v30
	v_pk_fma_f32 v[32:33], v[40:41], v[238:239], v[2:3]
	v_lshlrev_b32_e32 v40, 16, v22
	v_and_b32_e32 v41, 0xffff0000, v22
	v_lshlrev_b32_e32 v2, 16, v14
	v_and_b32_e32 v3, 0xffff0000, v14
	v_pk_add_f32 v[40:41], v[40:41], v[42:43]
	v_lshlrev_b32_e32 v42, 16, v29
	v_pk_fma_f32 v[40:41], v[40:41], 0.5, v[2:3] op_sel_hi:[1,0,1] neg_lo:[0,0,1] neg_hi:[0,0,1]
	v_and_b32_e32 v43, 0xffff0000, v29
	v_pk_fma_f32 v[36:37], v[40:41], v[242:243], v[2:3]
	v_lshlrev_b32_e32 v40, 16, v21
	v_and_b32_e32 v41, 0xffff0000, v21
	v_lshlrev_b32_e32 v2, 16, v13
	v_and_b32_e32 v3, 0xffff0000, v13
	v_pk_add_f32 v[40:41], v[40:41], v[42:43]
	v_lshlrev_b32_e32 v42, 16, v31
	v_pk_fma_f32 v[40:41], v[40:41], 0.5, v[2:3] op_sel_hi:[1,0,1] neg_lo:[0,0,1] neg_hi:[0,0,1]
	v_and_b32_e32 v43, 0xffff0000, v31
	v_pk_fma_f32 v[34:35], v[40:41], v[240:241], v[2:3]
	v_lshlrev_b32_e32 v40, 16, v23
	v_and_b32_e32 v41, 0xffff0000, v23
	v_lshlrev_b32_e32 v2, 16, v15
	v_and_b32_e32 v3, 0xffff0000, v15
	v_pk_add_f32 v[40:41], v[40:41], v[42:43]
	s_add_i32 s62, s65, 1
	v_pk_fma_f32 v[40:41], v[40:41], 0.5, v[2:3] op_sel_hi:[1,0,1] neg_lo:[0,0,1] neg_hi:[0,0,1]
	s_nop 0
	v_pk_fma_f32 v[38:39], v[40:41], v[244:245], v[2:3]
	ds_write_b128 v87, v[32:35] offset:32
	ds_write_b128 v87, v[36:39] offset:48
	s_waitcnt lgkmcnt(0)
	s_barrier
	ds_read_b128 v[32:35], v89 offset:768
	ds_read_b128 v[36:39], v89 offset:784
	ds_read_b128 v[40:43], v89 offset:896
	s_waitcnt lgkmcnt(2)
	v_mul_f32_e64 v0, |v32|, s98
	v_exp_f32_e32 v2, v0
	v_mul_f32_e64 v0, |v33|, s98
	v_exp_f32_e32 v3, v0
	v_add_f32_e32 v0, 1.0, v2
	v_rcp_f32_e32 v44, v0
	v_add_f32_e32 v0, 1.0, v3
	v_rcp_f32_e32 v45, v0
	v_mul_f32_e64 v0, |v34|, s98
	v_pk_add_f32 v[2:3], v[2:3], 1.0 op_sel_hi:[1,0] neg_lo:[1,0] neg_hi:[1,0]
	v_pk_mul_f32 v[2:3], v[2:3], v[44:45]
	v_exp_f32_e32 v44, v0
	v_mul_f32_e64 v0, |v35|, s98
	v_exp_f32_e32 v45, v0
	v_bfi_b32 v0, s99, v3, v33
	v_add_f32_e32 v3, 1.0, v44
	v_rcp_f32_e32 v46, v3
	v_add_f32_e32 v3, 1.0, v45
	v_bfi_b32 v2, s99, v2, v32
	v_rcp_f32_e32 v47, v3
	v_cvt_pk_bf16_f32 v32, v2, v0
	s_waitcnt lgkmcnt(1)
	v_mul_f32_e64 v0, |v36|, s98
	v_pk_add_f32 v[2:3], v[44:45], 1.0 op_sel_hi:[1,0] neg_lo:[1,0] neg_hi:[1,0]
	v_exp_f32_e32 v44, v0
	v_mul_f32_e64 v0, |v37|, s98
	v_pk_mul_f32 v[2:3], v[2:3], v[46:47]
	v_exp_f32_e32 v45, v0
	s_waitcnt lgkmcnt(0)
	v_cvt_pk_bf16_f32 v40, v40, v41
	v_cvt_pk_bf16_f32 v41, v42, v43
	v_bfi_b32 v0, s99, v3, v35
	v_add_f32_e32 v3, 1.0, v44
	v_rcp_f32_e32 v46, v3
	v_bfi_b32 v2, s99, v2, v34
	v_cvt_pk_bf16_f32 v33, v2, v0
	v_mul_f32_e64 v0, |v38|, s98
	v_add_f32_e32 v3, 1.0, v45
	v_rcp_f32_e32 v47, v3
	v_pk_add_f32 v[2:3], v[44:45], 1.0 op_sel_hi:[1,0] neg_lo:[1,0] neg_hi:[1,0]
	v_exp_f32_e32 v44, v0
	v_mul_f32_e64 v0, |v39|, s98
	v_exp_f32_e32 v45, v0
	v_pk_mul_f32 v[2:3], v[2:3], v[46:47]
	v_bfi_b32 v0, s99, v3, v37
	v_add_f32_e32 v3, 1.0, v44
	v_rcp_f32_e32 v46, v3
	v_add_f32_e32 v3, 1.0, v45
	v_rcp_f32_e32 v47, v3
	v_bfi_b32 v2, s99, v2, v36
	v_cvt_pk_bf16_f32 v34, v2, v0
	v_pk_add_f32 v[2:3], v[44:45], 1.0 op_sel_hi:[1,0] neg_lo:[1,0] neg_hi:[1,0]
	v_pk_mul_f32 v[2:3], v[2:3], v[46:47]
	v_bfi_b32 v0, s99, v3, v39
	v_bfi_b32 v2, s99, v2, v38
	ds_read_b128 v[36:39], v91
	ds_read_b128 v[44:47], v89 offset:912
	v_cvt_pk_bf16_f32 v35, v2, v0
	ds_read_b128 v[58:61], v91 offset:5120
	ds_read2st64_b32 v[2:3], v207 offset0:64 offset1:65
	s_waitcnt lgkmcnt(3)
; #define LAS __attribute__((address_space(3)))
; __device__ __forceinline__ float bf_lo(unsigned w) { return __uint_as_float(w << 16); }
; __device__ void rwkv_chunk_phase(const Params& p, int l, LAS unsigned char* lds) {
;     ...
;                 const f32x4 cw = __builtin_amdgcn_mfma_f32_16x16x32_bf16(__builtin_bit_cast(bf16x8, aw), bw, z4, 0, 0, 0);
;                 const f32x4 ca = __builtin_amdgcn_mfma_f32_16x16x32_bf16(__builtin_bit_cast(bf16x8, aa), ba, z4, 0, 0, 0);
;                 const int col = ct * 16 + r16; const float w0c = c_s[col], a0c = c_s[64 + col];
;                 f32x4 lwv, lo;
; #pragma unroll
;                 for (int j = 0; j < 4; ++j) { const int tr_ = rt * 16 + quad * 4 + j; lwv[j] = -__expf(-softplus_(-(cw[j] + w0c)) - 0.5f); y_s[tr_ * 64 + col] = lwv[j]; lg_s[tr_ * 64 + col] = ca[j] + a0c; }
;                 const unsigned h01 = cvt_pk_bf16(lwv[0], lwv[1]), h23 = cvt_pk_bf16(lwv[2], lwv[3]);
;                 lo[0] = lwv[0] - bf_lo(h01); lo[1] = lwv[1] - bf_hi(h01); lo[2] = lwv[2] - bf_lo(h23); lo[3] = lwv[3] - bf_hi(h23);
;                 u32x2 hw; hw.x = h01; hw.y = h23; *(LAS u32x2*)(lwT_hi + col * 40 + rt * 16 + quad * 4) = hw; st_bf4(lwT_lo + col * 40 + rt * 16 + quad * 4, lo); }
;             LBAR();
;             {   const f32x4 wp = *(const LAS f32x4*)(y_s + tok * 64 + j0), ap = *(const LAS f32x4*)(lg_s + tok * 64 + j0);
;                 r4 = *(const LAS f32x4*)(sh_s + tok * 256 + j0); const f32x4 kv4 = *(const LAS f32x4*)(sh_s + tok * 256 + 64 + j0); v4 = *(const LAS f32x4*)(sh_s + tok * 256 + 128 + j0);
;                 float ss = 0.f, bs = 0.f;
; #pragma unroll
;                 for (int j = 0; j < 4; ++j) { kk4[j] = kv4[j] * c_s[128 + j0 + j]; ss += kk4[j] * kk4[j]; }
;                 ss = red16d(ss);
;                 const float rn_ = rsqrtf(ss + 1e-12f);
; #pragma unroll
;                 for (int j = 0; j < 4; ++j) {
;                     const float a = sigmoid_(ap[j]);
;                     lw4[j] = wp[j];
;                     kk4[j] *= rn_; b4[j] = kk4[j] * a;
;                     kd4[j] = kv4[j] * (1.0f + (a - 1.0f) * c_s[192 + j0 + j]);
;                     bs += r4[j] * kd4[j] * c_s[256 + j0 + j];
;                 }
;                 bs = red16d(bs);
;                 if (dir == 0 && cg == 0) BON[(t0 + tokm) * 8 + h] = bs;
	v_mfma_f32_16x16x32_bf16 v[32:35], v[32:35], v[36:39], 0
	s_waitcnt lgkmcnt(2)
	v_cvt_pk_bf16_f32 v42, v44, v45
	v_cvt_pk_bf16_f32 v43, v46, v47
	s_waitcnt lgkmcnt(0)
	s_nop 3
	v_add_f32_e32 v0, v32, v2
	v_mul_f32_e64 v32, |v0|, s97
	v_exp_f32_e32 v32, v32
	v_add_f32_e32 v33, v33, v2
	v_max_f32_e64 v0, -v0, 0
	v_add_f32_e32 v34, v34, v2
	v_add_f32_e32 v32, 1.0, v32
	v_add_f32_e32 v2, v35, v2
	v_mul_f32_e64 v35, |v2|, s97
	v_log_f32_e32 v32, v32
	v_mfma_f32_16x16x32_bf16 v[36:39], v[40:43], v[58:61], 0
	v_exp_f32_e32 v35, v35
	v_max_f32_e64 v2, -v2, 0
	v_mul_f32_e32 v40, 0x3f317217, v32
	v_fma_f32 v40, v32, s48, -v40
	v_fmac_f32_e32 v40, 0x3377d1cf, v32
	v_fmac_f32_e32 v40, 0x3f317217, v32
	v_add_f32_e32 v35, 1.0, v35
	v_add_f32_e32 v37, v37, v3
	v_mov_b32_e32 v32, v40
	v_mul_f32_e64 v40, |v33|, s97
	v_exp_f32_e32 v40, v40
	v_add_f32_e32 v0, v0, v32
	v_sub_f32_e32 v0, -0.5, v0
	v_mul_f32_e32 v0, 0x3fb8aa3b, v0
	v_add_f32_e32 v32, 1.0, v40
	v_max_f32_e64 v33, -v33, 0
	v_add_f32_e32 v38, v38, v3
	v_log_f32_e32 v40, v32
	v_exp_f32_e32 v32, v0
	v_add_f32_e32 v0, v36, v3
	v_add_f32_e32 v39, v39, v3
	v_mul_f32_e32 v36, 0x3f317217, v40
	v_fma_f32 v36, v40, s48, -v36
	v_fmac_f32_e32 v36, 0x3377d1cf, v40
	v_fmac_f32_e32 v36, 0x3f317217, v40
	v_mul_f32_e64 v40, |v34|, s97
	v_exp_f32_e32 v40, v40
	v_add_f32_e32 v33, v33, v36
	v_max_f32_e64 v34, -v34, 0
	v_sub_f32_e32 v33, -0.5, v33
	v_add_f32_e32 v36, 1.0, v40
	v_mul_f32_e32 v33, 0x3fb8aa3b, v33
	v_exp_f32_e32 v33, v33
	v_log_f32_e32 v36, v36
	s_nop 0
	v_mul_f32_e32 v40, 0x3f317217, v36
	v_fma_f32 v40, v36, s48, -v40
	v_fmac_f32_e32 v40, 0x3377d1cf, v36
	v_fmac_f32_e32 v40, 0x3f317217, v36
	v_mov_b32_e32 v36, v40
	v_add_f32_e32 v34, v34, v36
	v_sub_f32_e32 v34, -0.5, v34
	v_log_f32_e32 v35, v35
	v_mul_f32_e32 v34, 0x3fb8aa3b, v34
	v_exp_f32_e32 v34, v34
	v_xor_b32_e32 v40, 0x80000000, v32
	v_mul_f32_e32 v36, 0x3f317217, v35
	v_fma_f32 v36, v35, s48, -v36
	v_fmac_f32_e32 v36, 0x3377d1cf, v35
	v_fmac_f32_e32 v36, 0x3f317217, v35
	v_mov_b32_e32 v35, v36
	v_add_f32_e32 v2, v2, v35
	v_sub_f32_e32 v2, -0.5, v2
	v_mul_f32_e32 v2, 0x3fb8aa3b, v2
	v_exp_f32_e32 v35, v2
	v_pk_add_f32 v[2:3], v[32:33], 0 neg_lo:[1,1] neg_hi:[1,1]
	v_xor_b32_e32 v36, 0x80000000, v33
	v_cvt_pk_bf16_f32 v2, v2, v3
	ds_write2st64_b32 v148, v0, v40 offset0:82 offset1:114
	ds_write2st64_b32 v150, v37, v36 offset0:82 offset1:114
	v_lshlrev_b32_e32 v36, 16, v2
	v_and_b32_e32 v37, 0xffff0000, v2
	v_pk_add_f32 v[32:33], v[32:33], v[36:37] neg_lo:[1,1] neg_hi:[1,1]
	v_pk_add_f32 v[36:37], v[34:35], 0 neg_lo:[1,1] neg_hi:[1,1]
	v_xor_b32_e32 v3, 0x80000000, v34
	v_xor_b32_e32 v0, 0x80000000, v35
	ds_write2st64_b32 v152, v38, v3 offset0:82 offset1:114
	ds_write2st64_b32 v154, v39, v0 offset0:82 offset1:114
	v_cvt_pk_bf16_f32 v3, v36, v37
	v_lshlrev_b32_e32 v36, 16, v3
	v_and_b32_e32 v37, 0xffff0000, v3
	v_pk_add_f32 v[34:35], v[34:35], v[36:37] neg_lo:[1,1] neg_hi:[1,1]
	ds_write_b64 v92, v[2:3]
	v_cvt_pk_bf16_f32 v2, v32, v33
	v_cvt_pk_bf16_f32 v3, v34, v35
	ds_write_b64 v93, v[2:3]
	s_waitcnt lgkmcnt(0)
	s_barrier
	ds_read_b128 v[36:39], v94 offset:29184
	ds_read_b128 v[32:35], v94 offset:20992
	ds_read_b128 v[44:47], v96 offset:17408
	ds_read_b128 v[218:221], v96 offset:17152
	ds_read_b128 v[40:43], v95
	ds_read_b128 v[222:225], v95 offset:256
	s_and_b64 s[24:25], s[4:5], exec
	s_cselect_b32 s24, s62, s63
	s_lshl_b32 s24, s24, 5
	s_waitcnt lgkmcnt(4)
	v_mul_f32_e32 v0, 0xbfb8aa3b, v32
	v_exp_f32_e32 v0, v0
	v_mul_f32_e32 v2, 0xbfb8aa3b, v33
	v_exp_f32_e32 v2, v2
	s_or_b32 s24, s60, s24
	v_add_f32_e32 v0, 1.0, v0
	v_rcp_f32_e32 v64, v0
	v_add_f32_e32 v0, 1.0, v2
	v_rcp_f32_e32 v65, v0
	s_mov_b32 s25, s61
	v_lshl_add_u64 v[58:59], s[24:25], 0, v[52:53]
	v_pk_add_f32 v[2:3], v[64:65], -1.0 op_sel_hi:[1,0]
	s_waitcnt lgkmcnt(2)
	v_pk_fma_f32 v[2:3], v[2:3], v[218:219], 1.0 op_sel_hi:[1,1,0]
	s_waitcnt lgkmcnt(0)
	v_pk_mul_f32 v[62:63], v[222:223], v[2:3]
	v_mul_f32_e32 v3, 0xbfb8aa3b, v35
	v_mul_f32_e32 v0, v40, v62
	v_fma_f32 v0, v44, v0, 0
	v_mul_f32_e32 v2, v41, v63
	v_fmac_f32_e32 v0, v45, v2
	v_mul_f32_e32 v2, 0xbfb8aa3b, v34
	ds_read_b128 v[32:35], v95 offset:512
	ds_read_b128 v[226:229], v96 offset:16896
	v_exp_f32_e32 v2, v2
	v_exp_f32_e32 v3, v3
	v_add_f32_e32 v2, 1.0, v2
	s_waitcnt lgkmcnt(0)
	v_pk_mul_f32 v[70:71], v[222:223], v[226:227]
	v_rcp_f32_e32 v66, v2
	v_add_f32_e32 v2, 1.0, v3
	v_pk_mul_f32 v[68:69], v[224:225], v[228:229]
	v_pk_mul_f32 v[44:45], v[70:71], v[70:71]
	v_rcp_f32_e32 v67, v2
	v_pk_mul_f32 v[2:3], v[68:69], v[68:69]
	v_add_f32_e32 v44, v44, v45
	v_add_f32_e32 v2, v44, v2
	v_add_f32_e32 v2, v2, v3
	s_nop 1
	v_add_f32_dpp v2, v2, v2 quad_perm:[1,0,3,2] row_mask:0xf bank_mask:0xf bound_ctrl:1
	s_nop 1
	v_add_f32_dpp v2, v2, v2 quad_perm:[2,3,0,1] row_mask:0xf bank_mask:0xf bound_ctrl:1
	s_nop 1
	v_add_f32_dpp v51, v2, v2 row_half_mirror row_mask:0xf bank_mask:0xf bound_ctrl:1
	v_pk_add_f32 v[2:3], v[66:67], -1.0 op_sel_hi:[1,0]
	s_nop 0
	v_pk_fma_f32 v[2:3], v[2:3], v[220:221], 1.0 op_sel_hi:[1,1,0]
	v_mov_b32_dpp v218, v51 row_mirror row_mask:0xf bank_mask:0xf bound_ctrl:1
	v_pk_mul_f32 v[60:61], v[224:225], v[2:3]
	s_nop 0
	v_mul_f32_e32 v2, v42, v60
	v_fmac_f32_e32 v0, v46, v2
	v_mul_f32_e32 v2, v43, v61
	v_fmac_f32_e32 v0, v47, v2
	s_nop 1
	v_add_f32_dpp v0, v0, v0 quad_perm:[1,0,3,2] row_mask:0xf bank_mask:0xf bound_ctrl:1
	s_nop 1
	v_add_f32_dpp v0, v0, v0 quad_perm:[2,3,0,1] row_mask:0xf bank_mask:0xf bound_ctrl:1
	s_nop 1
	v_add_f32_dpp v0, v0, v0 row_half_mirror row_mask:0xf bank_mask:0xf bound_ctrl:1
	s_nop 1
	v_mov_b32_dpp v2, v0 row_mirror row_mask:0xf bank_mask:0xf bound_ctrl:1
	s_and_saveexec_b64 s[24:25], s[6:7]
	s_cbranch_execz .LBB0_323
	v_add_f32_e32 v0, v0, v2
	v_lshlrev_b64 v[2:3], 5, v[58:59]
	v_lshl_add_u64 v[2:3], s[40:41], 0, v[2:3]
	global_store_dword v[2:3], v0, off

; __device__ __forceinline__ unsigned cvt_pk_bf16(float lo, float hi) { const f32x2_t v = {lo, hi}; const bf16x2_t b = __builtin_convertvector(v, bf16x2_t); return __builtin_bit_cast(unsigned, b); }
; __device__ void fnet_nyquist_phase(const Params& p) {
;     ...
;     for (int pr = gw; pr < NB_ * 512; pr += nw) {
;         const int b = pr >> 9, n = pr & 511;
;         const bf16_t* a = FT + ((size_t)(b * 2) * 512 + n) * SEQ_;
;         float acc = 0.f;
; #pragma unroll
;         for (int i = 0; i < 4; ++i) { float f[8]; unpack8(*(const uint4*)(a + (lane + 64 * i) * 8), f); acc += (f[0] - f[1]) + (f[2] - f[3]) + (f[4] - f[5]) + (f[6] - f[7]); }
; #pragma unroll
;         for (int o = 32; o >= 1; o >>= 1) acc += __shfl_xor(acc, o);
;         if (lane == 0) { const float y = acc * (1.0f / 512.0f); YB[((size_t)b * SEQ_ + 1024) * 512 + n] = (bf16_t)(cvt_pk_bf16(y, y) & 0xffffu); }
;     }
.LBB0_393:
	v_ashrrev_i32_e32 v4, 9, v6
	v_lshlrev_b32_e32 v14, 1, v4
	v_ashrrev_i32_e32 v15, 31, v14
	v_and_b32_e32 v13, 0x1ff, v6
	v_lshlrev_b64 v[14:15], 21, v[14:15]
	v_lshl_add_u64 v[14:15], s[6:7], 0, v[14:15]
	v_lshlrev_b32_e32 v0, 12, v13
	v_lshl_add_u64 v[14:15], v[14:15], 0, v[0:1]
	s_waitcnt lgkmcnt(0)
	v_mov_b32_e32 v3, v1
	v_lshl_add_u64 v[18:19], v[14:15], 0, v[2:3]
	global_load_dwordx4 v[14:17], v[18:19], off
	global_load_dwordx4 v[24:27], v[18:19], off offset:1024
	global_load_dwordx4 v[28:31], v[18:19], off offset:2048
	global_load_dwordx4 v[32:35], v[18:19], off offset:3072
	s_waitcnt vmcnt(3)
	v_lshlrev_b32_e32 v0, 16, v14
	v_and_b32_e32 v3, 0xffff0000, v14
	v_lshlrev_b32_e32 v5, 16, v15
	v_and_b32_e32 v14, 0xffff0000, v15
	v_lshlrev_b32_e32 v15, 16, v16
	v_and_b32_e32 v16, 0xffff0000, v16
	v_sub_f32_e32 v0, v0, v3
	v_sub_f32_e32 v3, v5, v14
	v_lshlrev_b32_e32 v20, 16, v17
	v_and_b32_e32 v17, 0xffff0000, v17
	v_add_f32_e32 v0, v0, v3
	v_sub_f32_e32 v3, v15, v16
	v_add_f32_e32 v0, v0, v3
	v_sub_f32_e32 v3, v20, v17
	v_add_f32_e32 v0, v0, v3
	v_add_f32_e32 v0, 0, v0
	s_waitcnt vmcnt(2)
	v_lshlrev_b32_e32 v3, 16, v24
	v_and_b32_e32 v5, 0xffff0000, v24
	v_lshlrev_b32_e32 v14, 16, v25
	v_and_b32_e32 v15, 0xffff0000, v25
	v_lshlrev_b32_e32 v20, 16, v26
	v_and_b32_e32 v16, 0xffff0000, v26
	v_sub_f32_e32 v3, v3, v5
	v_sub_f32_e32 v5, v14, v15
	v_lshlrev_b32_e32 v21, 16, v27
	v_and_b32_e32 v17, 0xffff0000, v27
	v_add_f32_e32 v3, v3, v5
	v_sub_f32_e32 v5, v20, v16
	v_add_f32_e32 v3, v3, v5
	v_sub_f32_e32 v5, v21, v17
	v_add_f32_e32 v3, v3, v5
	v_add_f32_e32 v0, v0, v3
	s_waitcnt vmcnt(1)
	v_lshlrev_b32_e32 v3, 16, v28
	v_and_b32_e32 v5, 0xffff0000, v28
	v_lshlrev_b32_e32 v14, 16, v29
	v_and_b32_e32 v15, 0xffff0000, v29
	v_lshlrev_b32_e32 v20, 16, v30
	v_and_b32_e32 v16, 0xffff0000, v30
	v_sub_f32_e32 v3, v3, v5
	v_sub_f32_e32 v5, v14, v15
	v_lshlrev_b32_e32 v21, 16, v31
	v_and_b32_e32 v17, 0xffff0000, v31
	v_add_f32_e32 v3, v3, v5
	v_sub_f32_e32 v5, v20, v16
	v_add_f32_e32 v3, v3, v5
	v_sub_f32_e32 v5, v21, v17
	v_add_f32_e32 v3, v3, v5
	v_add_f32_e32 v0, v0, v3
	s_waitcnt vmcnt(0)
	v_lshlrev_b32_e32 v3, 16, v32
	v_and_b32_e32 v5, 0xffff0000, v32
	v_lshlrev_b32_e32 v14, 16, v33
	v_and_b32_e32 v15, 0xffff0000, v33
	v_lshlrev_b32_e32 v18, 16, v34
	v_and_b32_e32 v16, 0xffff0000, v34
	v_sub_f32_e32 v3, v3, v5
	v_sub_f32_e32 v5, v14, v15
	v_lshlrev_b32_e32 v19, 16, v35
	v_and_b32_e32 v17, 0xffff0000, v35
	v_add_f32_e32 v3, v3, v5
	v_sub_f32_e32 v5, v18, v16
	v_add_f32_e32 v3, v3, v5
	v_sub_f32_e32 v5, v19, v17
	v_add_f32_e32 v3, v3, v5
	v_add_f32_e32 v0, v0, v3
	ds_bpermute_b32 v3, v7, v0
	s_waitcnt lgkmcnt(0)
	v_add_f32_e32 v0, v0, v3
	ds_bpermute_b32 v3, v8, v0
	s_waitcnt lgkmcnt(0)
	v_add_f32_e32 v0, v0, v3
	ds_bpermute_b32 v3, v9, v0
	s_waitcnt lgkmcnt(0)
	v_add_f32_e32 v0, v0, v3
	ds_bpermute_b32 v3, v10, v0
	s_waitcnt lgkmcnt(0)
	v_add_f32_e32 v0, v0, v3
	ds_bpermute_b32 v3, v11, v0
	s_waitcnt lgkmcnt(0)
	v_add_f32_e32 v0, v0, v3
	ds_bpermute_b32 v3, v12, v0
	s_and_saveexec_b64 s[2:3], vcc
	s_cbranch_execz .LBB0_392
	s_waitcnt lgkmcnt(0)
	v_add_f32_e32 v0, v0, v3
	v_ashrrev_i32_e32 v5, 31, v4
	v_mul_f32_e32 v0, 0x3b000000, v0
	v_lshlrev_b64 v[4:5], 21, v[4:5]
	v_cvt_pk_bf16_f32 v3, v0, s0
	v_lshl_add_u64 v[4:5], s[8:9], 0, v[4:5]
	v_lshlrev_b32_e32 v0, 1, v13
	v_lshl_add_u64 v[4:5], v[4:5], 0, v[0:1]
	global_store_short v[4:5], v3, off
	s_branch .LBB0_392

; #define LAS __attribute__((address_space(3)))
; __device__ __forceinline__ uint4 pack8(const float (&f)[8]) { uint4 r; r.x = cvt_pk_bf16(f[0], f[1]); r.y = cvt_pk_bf16(f[2], f[3]); r.z = cvt_pk_bf16(f[4], f[5]); r.w = cvt_pk_bf16(f[6], f[7]); return r; }
; __device__ void gla_chunk_phase(const Params& p, int l, LAS unsigned char* lds) {
;     ...
;             {   const f32x4 b0 = *(const LAS f32x4*)(b_s + ltok * 64 + lc8), b1 = *(const LAS f32x4*)(b_s + ltok * 64 + lc8 + 4);
;                 const f32x4 d0 = *(const LAS f32x4*)(dk_s + lc8), d1 = *(const LAS f32x4*)(dk_s + lc8 + 4);
;                 float qv[8], kv[8], ktv[8];
; #pragma unroll
;                 for (int j = 0; j < 8; ++j) {
;                     const float bb = (j < 4) ? b0[j & 3] : b1[j & 3], dkj = (j < 4) ? d0[j & 3] : d1[j & 3];
;                     const float e = __expf(bb), einv = __builtin_amdgcn_rcpf(e);
;                     qv[j] = fq[j] * 0.125f * e; kv[j] = fk[j] * einv;
;                     ktv[j] = kv[j] * dkj;
;                 }
;                 const uint4 q4 = pack8(qv), k4 = pack8(kv), t4 = pack8(ktv), v4 = pack8(fv);
;                 *(LAS u32x4*)(qd + ltok * 72 + lc8) = (u32x4){q4.x, q4.y, q4.z, q4.w}; *(LAS u32x4*)(kd + ltok * 72 + lc8) = (u32x4){k4.x, k4.y, k4.z, k4.w};
;                 *(LAS u32x4*)(ktT + ltok * 72 + lc8) = (u32x4){t4.x, t4.y, t4.z, t4.w}; *(LAS u32x4*)(vT + ltok * 72 + lc8) = (u32x4){v4.x, v4.y, v4.z, v4.w}; }
.LBB0_435:
	s_or_b64 exec, exec, s[20:21]
	s_waitcnt lgkmcnt(0)
	s_barrier
	s_waitcnt vmcnt(0)
	s_nop 0
	v_lshlrev_b32_e32 v44, 16, v38
	v_and_b32_e32 v45, 0xffff0000, v38
	v_lshlrev_b32_e32 v62, 16, v39
	v_and_b32_e32 v63, 0xffff0000, v39
	v_lshlrev_b32_e32 v120, 16, v40
	v_and_b32_e32 v121, 0xffff0000, v40
	v_lshlrev_b32_e32 v122, 16, v41
	v_and_b32_e32 v123, 0xffff0000, v41
	v_lshlrev_b32_e32 v124, 16, v30
	v_and_b32_e32 v125, 0xffff0000, v30
	v_lshlrev_b32_e32 v126, 16, v31
	v_and_b32_e32 v127, 0xffff0000, v31
	v_lshlrev_b32_e32 v128, 16, v32
	v_and_b32_e32 v129, 0xffff0000, v32
	v_lshlrev_b32_e32 v30, 16, v33
	v_and_b32_e32 v31, 0xffff0000, v33
	v_lshlrev_b32_e32 v53, 16, v34
	v_and_b32_e32 v115, 0xffff0000, v34
	v_lshlrev_b32_e32 v148, 16, v35
	v_and_b32_e32 v149, 0xffff0000, v35
	v_lshlrev_b32_e32 v150, 16, v36
	v_and_b32_e32 v151, 0xffff0000, v36
	v_lshlrev_b32_e32 v152, 16, v37
	v_and_b32_e32 v153, 0xffff0000, v37
	ds_read_b128 v[32:35], v76
	ds_read_b128 v[36:39], v76 offset:16
	ds_read_b128 v[40:43], v77
	ds_read_b128 v[116:119], v77 offset:16
	v_pk_mul_f32 v[44:45], v[44:45], s[74:75] op_sel_hi:[1,0]
	s_waitcnt lgkmcnt(3)
	v_mul_f32_e32 v32, 0x3fb8aa3b, v32
	v_mul_f32_e32 v33, 0x3fb8aa3b, v33
	v_exp_f32_e32 v32, v32
	v_exp_f32_e32 v33, v33
	v_mul_f32_e32 v34, 0x3fb8aa3b, v34
	v_mul_f32_e32 v35, 0x3fb8aa3b, v35
	v_rcp_f32_e32 v138, v32
	v_rcp_f32_e32 v139, v33
	v_exp_f32_e32 v34, v34
	v_exp_f32_e32 v35, v35
	s_waitcnt lgkmcnt(2)
	v_mul_f32_e32 v36, 0x3fb8aa3b, v36
	v_mul_f32_e32 v37, 0x3fb8aa3b, v37
	v_pk_mul_f32 v[32:33], v[44:45], v[32:33]
	v_pk_mul_f32 v[44:45], v[138:139], v[124:125]
	v_rcp_f32_e32 v124, v34
	v_rcp_f32_e32 v125, v35
	v_exp_f32_e32 v36, v36
	v_exp_f32_e32 v37, v37
	v_pk_mul_f32 v[62:63], v[62:63], s[74:75] op_sel_hi:[1,0]
	v_mul_f32_e32 v38, 0x3fb8aa3b, v38
	v_mul_f32_e32 v39, 0x3fb8aa3b, v39
	v_pk_mul_f32 v[34:35], v[62:63], v[34:35]
	v_pk_mul_f32 v[62:63], v[124:125], v[126:127]
	v_rcp_f32_e32 v124, v36
	v_rcp_f32_e32 v125, v37
	v_exp_f32_e32 v38, v38
	v_exp_f32_e32 v39, v39
	v_pk_mul_f32 v[120:121], v[120:121], s[74:75] op_sel_hi:[1,0]
	v_pk_mul_f32 v[122:123], v[122:123], s[74:75] op_sel_hi:[1,0]
	v_pk_mul_f32 v[36:37], v[120:121], v[36:37]
	v_pk_mul_f32 v[120:121], v[124:125], v[128:129]
	v_rcp_f32_e32 v124, v38
	v_rcp_f32_e32 v125, v39
	v_pk_mul_f32 v[38:39], v[122:123], v[38:39]
	s_waitcnt lgkmcnt(1)
	v_pk_mul_f32 v[40:41], v[40:41], v[44:45]
	v_pk_mul_f32 v[42:43], v[42:43], v[62:63]
	v_pk_mul_f32 v[122:123], v[124:125], v[30:31]
	s_waitcnt lgkmcnt(0)
	v_pk_mul_f32 v[116:117], v[116:117], v[120:121]
	v_pk_mul_f32 v[118:119], v[118:119], v[122:123]
	v_cvt_pk_bf16_f32 v30, v32, v33
	v_cvt_pk_bf16_f32 v31, v34, v35
	v_cvt_pk_bf16_f32 v32, v36, v37
	v_cvt_pk_bf16_f32 v33, v38, v39
	v_cvt_pk_bf16_f32 v34, v44, v45
	v_cvt_pk_bf16_f32 v35, v62, v63
	v_cvt_pk_bf16_f32 v36, v120, v121
	v_cvt_pk_bf16_f32 v37, v122, v123
	v_cvt_pk_bf16_f32 v38, v40, v41
	v_cvt_pk_bf16_f32 v39, v42, v43
	v_cvt_pk_bf16_f32 v40, v116, v117
	v_cvt_pk_bf16_f32 v41, v118, v119
	v_cvt_pk_bf16_f32 v42, v53, v115
	v_cvt_pk_bf16_f32 v43, v148, v149
	v_cvt_pk_bf16_f32 v44, v150, v151
	v_cvt_pk_bf16_f32 v45, v152, v153
	ds_write_b128 v50, v[30:33] offset:16384
	ds_write_b128 v50, v[34:37] offset:25600
	ds_write_b128 v50, v[38:41] offset:34816
	ds_write_b128 v50, v[42:45] offset:44032
	s_waitcnt lgkmcnt(0)
	s_barrier
; __device__ void gla_chunk_phase(const Params& p, int l, LAS unsigned char* lds) {
;     ...
;             f32x4 oacc[2] = {{0.f, 0.f, 0.f, 0.f}, {0.f, 0.f, 0.f, 0.f}};
;             {
;                 f32x4 sc[2] = {{0.f, 0.f, 0.f, 0.f}, {0.f, 0.f, 0.f, 0.f}};
;                 const f32x4 dkv = *(const LAS f32x4*)(dk_s + tr * 16 + quad * 4);
;                 sacc[0] *= dkv; sacc[1] *= dkv;
;                 const int arow = (tr * 16 + r16) * 72 + quad * 8;
; #pragma unroll
;                 for (int ks = 0; ks < 2; ++ks) {
;                     const bf16x8 a_kd = *(const LAS bf16x8*)(kd + arow + ks * 32), a_st = *(const LAS bf16x8*)(stT + arow + ks * 32), a_kt = trfrag(ktT, 72, ks * 32, tr * 16, lane);
; #pragma unroll
;                     for (int t = 0; t < 2; ++t) { const int brow = ((tcb + t) * 16 + r16) * 72 + ks * 32 + quad * 8;
;                         const bf16x8 b_qd = *(const LAS bf16x8*)(qd + brow), b_vT = trfrag(vT, 72, ks * 32, (tcb + t) * 16, lane);
;                         sc[t] = __builtin_amdgcn_mfma_f32_16x16x32_bf16(a_kd, b_qd, sc[t], 0, 0, 0);
;                         oacc[t] = __builtin_amdgcn_mfma_f32_16x16x32_bf16(a_st, b_qd, oacc[t], 0, 0, 0);
;                         sacc[t] = __builtin_amdgcn_mfma_f32_16x16x32_bf16(a_kt, b_vT, sacc[t], 0, 0, 0); } }
; #pragma unroll
;                 for (int t = 0; t < 2; ++t) { const int lrow = (tcb + t) * 16 + r16; float pv[4];
; #pragma unroll
;                     for (int j = 0; j < 4; ++j) { const int m = tr * 16 + quad * 4 + j; const bool keep = dir ? (lrow > m) : (lrow >= m); pv[j] = keep ? sc[t][j] : 0.f; }
;                     u32x2 pw; pw.x = cvt_pk_bf16(pv[0], pv[1]); pw.y = cvt_pk_bf16(pv[2], pv[3]);
;                     *(LAS u32x2*)(Pm + lrow * 72 + tr * 16 + quad * 4) = pw; } }
;             LBAR();
;             {
;                 const int arow = (tr * 16 + r16) * 72 + quad * 8;
; #pragma unroll
;                 for (int ks = 0; ks < 2; ++ks) { const bf16x8 a_v = trfrag(vT, 72, ks * 32, tr * 16, lane);
; #pragma unroll
;                     for (int t = 0; t < 2; ++t) { const bf16x8 b_P = *(const LAS bf16x8*)(Pm + ((tcb + t) * 16 + r16) * 72 + ks * 32 + quad * 8);
;                         oacc[t] = __builtin_amdgcn_mfma_f32_16x16x32_bf16(a_v, b_P, oacc[t], 0, 0, 0); } }
; #pragma unroll
;                 for (int t = 0; t < 2; ++t) { const int cr = (tcb + t) * 16 + r16;
	ds_read_b128 v[30:33], v51
	v_add_u32_e32 v53, v79, v87
	v_add_u32_e32 v62, v81, v87
	v_add_u32_e32 v63, v81, v95
	v_add_u32_e32 v115, v79, v95
	s_waitcnt lgkmcnt(0)
	v_pk_mul_f32 v[24:25], v[24:25], v[32:33]
	v_pk_mul_f32 v[22:23], v[22:23], v[30:31]
	v_pk_mul_f32 v[28:29], v[28:29], v[32:33]
	v_pk_mul_f32 v[26:27], v[26:27], v[30:31]
	ds_read_b128 v[30:33], v78 offset:25600
	ds_read_b128 v[34:37], v78 offset:62464
	ds_read_b64_tr_b16 v[38:39], v88 offset:34816
	ds_read_b64_tr_b16 v[40:41], v88 offset:35392
	ds_read_b128 v[42:45], v53 offset:16384
	ds_read_b64_tr_b16 v[116:117], v89 offset:44032
	ds_read_b64_tr_b16 v[118:119], v89 offset:44608
	s_waitcnt lgkmcnt(0)
	v_mfma_f32_16x16x32_bf16 v[22:25], v[38:41], v[116:119], v[22:25]
	ds_read_b128 v[116:119], v110 offset:16384
	ds_read_b64_tr_b16 v[124:125], v90 offset:44032
	ds_read_b64_tr_b16 v[126:127], v90 offset:44608
	s_add_i32 s22, s41, -1
	s_add_i32 s23, s42, 1
	v_mfma_f32_16x16x32_bf16 v[120:123], v[30:33], v[42:45], 0
	s_and_b64 s[20:21], exec, s[76:77]
	s_cselect_b32 s20, s22, s23
	s_lshl_b32 s86, s20, 6
	v_mfma_f32_16x16x32_bf16 v[42:45], v[34:37], v[42:45], 0
	s_add_i32 s42, s42, -1
	s_add_i32 s41, s41, 1
	s_cmp_eq_u32 s42, -2
	s_waitcnt lgkmcnt(2)
	v_mfma_f32_16x16x32_bf16 v[30:33], v[30:33], v[116:119], 0
	v_mfma_f32_16x16x32_bf16 v[34:37], v[34:37], v[116:119], 0
	s_waitcnt lgkmcnt(0)
	v_mfma_f32_16x16x32_bf16 v[26:29], v[38:41], v[124:127], v[26:29]
	ds_read_b128 v[38:41], v78 offset:25664
	ds_read_b128 v[116:119], v78 offset:62528
	ds_read_b64_tr_b16 v[124:125], v91 offset:34816
	ds_read_b64_tr_b16 v[126:127], v91 offset:35392
	ds_read_b128 v[148:151], v53 offset:16448
	ds_read_b64_tr_b16 v[152:153], v92 offset:44032
	ds_read_b64_tr_b16 v[154:155], v92 offset:44608
	s_waitcnt lgkmcnt(2)
	v_mfma_f32_16x16x32_bf16 v[120:123], v[38:41], v[148:151], v[120:123]
	v_mfma_f32_16x16x32_bf16 v[42:45], v[116:119], v[148:151], v[42:45]
	s_waitcnt lgkmcnt(0)
	v_mfma_f32_16x16x32_bf16 v[22:25], v[124:127], v[152:155], v[22:25]
	ds_read_b128 v[148:151], v110 offset:16448
	ds_read_b64_tr_b16 v[152:153], v93 offset:44032
	ds_read_b64_tr_b16 v[154:155], v93 offset:44608
	s_waitcnt lgkmcnt(2)
	v_mfma_f32_16x16x32_bf16 v[30:33], v[38:41], v[148:151], v[30:33]
	v_cndmask_b32_e32 v38, 0, v120, vcc
	v_cndmask_b32_e64 v39, 0, v121, s[6:7]
	v_cndmask_b32_e64 v40, 0, v122, s[8:9]
	v_cndmask_b32_e64 v41, 0, v123, s[10:11]
	v_cvt_pk_bf16_f32 v38, v38, v39
	s_nop 2
	v_cndmask_b32_e64 v30, 0, v30, s[12:13]
	v_cndmask_b32_e64 v31, 0, v31, s[14:15]
	v_cndmask_b32_e64 v32, 0, v32, s[16:17]
	v_cndmask_b32_e64 v33, 0, v33, s[18:19]
	v_cvt_pk_bf16_f32 v39, v40, v41
	v_cvt_pk_bf16_f32 v30, v30, v31
	v_cvt_pk_bf16_f32 v31, v32, v33
	ds_write_b64 v62, v[38:39] offset:53248
	ds_write_b64 v63, v[30:31] offset:53248
	s_waitcnt lgkmcnt(0)
	s_barrier
	ds_read_b64_tr_b16 v[30:31], v111 offset:44032
	ds_read_b64_tr_b16 v[32:33], v111 offset:44608
	ds_read_b128 v[38:41], v53 offset:53248
	s_waitcnt lgkmcnt(0)
	v_mfma_f32_16x16x32_bf16 v[38:41], v[30:33], v[38:41], v[42:45]
	s_nop 2
	ds_read_b128 v[42:45], v115 offset:53248
	v_mfma_f32_16x16x32_bf16 v[34:37], v[116:119], v[148:151], v[34:37]
	s_waitcnt lgkmcnt(0)
	v_mfma_f32_16x16x32_bf16 v[30:33], v[30:33], v[42:45], v[34:37]
	s_nop 5
	ds_read_b64_tr_b16 v[34:35], v111 offset:48640
	ds_read_b64_tr_b16 v[36:37], v111 offset:49216
	ds_read_b128 v[42:45], v53 offset:53312
	s_waitcnt lgkmcnt(0)
	v_mfma_f32_16x16x32_bf16 v[38:41], v[34:37], v[42:45], v[38:41]
	ds_read_b128 v[42:45], v115 offset:53312
	v_mfma_f32_16x16x32_bf16 v[26:29], v[124:127], v[152:155], v[26:29]
	s_nop 5
	ds_write_b128 v112, v[38:41]
	v_mov_b64_e32 v[38:39], v[10:11]
	v_mov_b64_e32 v[40:41], v[12:13]
	s_waitcnt lgkmcnt(1)
	v_mfma_f32_16x16x32_bf16 v[30:33], v[34:37], v[42:45], v[30:33]
	v_cvt_pk_bf16_f32 v34, v22, v23
	v_cvt_pk_bf16_f32 v35, v24, v25
	ds_write_b64 v62, v[34:35] offset:62464
	s_nop 4
	ds_write_b128 v113, v[30:33]
	v_cvt_pk_bf16_f32 v30, v26, v27
	v_cvt_pk_bf16_f32 v31, v28, v29
	ds_write_b64 v63, v[30:31] offset:62464
	s_mov_b64 s[20:21], exec
	s_mov_b64 exec, s[44:45]
	ds_write_b128 v104, v[6:9]
	s_mov_b64 exec, s[20:21]
	s_waitcnt lgkmcnt(0)
	s_barrier
	ds_read_b128 v[30:33], v82
	ds_read_b128 v[34:37], v82 offset:16
	s_waitcnt lgkmcnt(1)
	v_cvt_pk_bf16_f32 v30, v30, v31
	v_cvt_pk_bf16_f32 v31, v32, v33
	s_waitcnt lgkmcnt(0)
	v_cvt_pk_bf16_f32 v32, v34, v35
	v_lshl_add_u64 v[34:35], v[60:61], 0, s[86:87]
	v_lshlrev_b64 v[34:35], 10, v[34:35]
	v_cvt_pk_bf16_f32 v33, v36, v37
	v_lshl_add_u64 v[34:35], v[56:57], 0, v[34:35]
	global_store_dwordx4 v[34:35], v[30:33], off
	v_mov_b64_e32 v[34:35], v[18:19]
	v_mov_b64_e32 v[36:37], v[20:21]
	v_mov_b64_e32 v[30:31], v[14:15]
	v_mov_b64_e32 v[32:33], v[16:17]
	s_cbranch_scc1 .LBB0_397
	s_branch .Lgla_top

; __device__ void gla_chunk_phase(const Params& p, int l, LAS unsigned char* lds) {
;     ...
;             if (ci + 1 < 32) {
;                 const int cn = dir ? 30 - ci : ci + 1; const size_t tb = (size_t)b * SEQ_ + cn * 64;
;                 const bf16_t* zr = ZG + (tb + ltokm) * ZGC;
;                 rq = *(const uint4*)(zr + h * 64 + lc8); rk = *(const uint4*)(zr + 256 + h * 64 + lc8); rv = *(const uint4*)(zr + 512 + h * 128 + vh * 64 + lc8);
;                 if (tid < 128) rd = *(const uint4*)(ZG + (tb + dtokm) * ZGC + dncol + dc8); }
.LBB0_438:
	s_or_b64 exec, exec, s[20:21]
	s_mov_b32 s100, 1
	s_branch .Lgla_T2
.Lgla_top:
	s_mov_b32 s100, 0
.Lgla_T2:
	s_cmp_eq_u32 s42, -1
	s_cbranch_scc1 .LBB0_442
	s_and_b64 s[20:21], exec, s[76:77]
	s_cselect_b32 s20, s41, s42
	s_lshl_b32 s20, s20, 6
	s_add_u32 s20, s92, s20
	s_addc_u32 s21, s93, 0
	v_lshl_add_u64 v[10:11], s[20:21], 0, v[54:55]
	v_mov_b64_e32 v[12:13], s[82:83]
	v_mad_u64_u32 v[18:19], s[22:23], v10, s47, v[12:13]
	v_mad_i32_i24 v19, v11, s47, v19
	s_mov_b32 s85, s87
	s_mov_b32 s35, s87
	v_lshl_add_u64 v[10:11], v[18:19], 0, s[84:85]
	v_lshl_add_u64 v[18:19], v[18:19], 0, s[34:35]
	s_mov_b32 s95, s87
	v_lshl_add_u64 v[18:19], v[18:19], 0, s[94:95]
	v_lshl_add_u64 v[14:15], v[10:11], 0, v[0:1]
	v_lshl_add_u64 v[18:19], v[18:19], 0, v[0:1]
	global_load_dwordx4 v[10:13], v[14:15], off
	s_nop 0
	global_load_dwordx4 v[14:17], v[14:15], off offset:512
	s_nop 0
	global_load_dwordx4 v[18:21], v[18:19], off offset:1024
	s_and_saveexec_b64 s[22:23], s[44:45]
	s_cbranch_execz .LBB0_441
	s_waitcnt lgkmcnt(0)
	v_or_b32_e32 v6, s20, v114
	v_mad_u64_u32 v[6:7], s[24:25], v6, s47, v[58:59]
	v_mad_i32_i24 v7, s21, v177, v7
	global_load_dwordx4 v[6:9], v[6:7], off

; #define LAS __attribute__((address_space(3)))
; __device__ __forceinline__ unsigned cvt_pk_bf16(float lo, float hi) { const f32x2_t v = {lo, hi}; const bf16x2_t b = __builtin_convertvector(v, bf16x2_t); return __builtin_bit_cast(unsigned, b); }
; __device__ __forceinline__ float bf_lo(unsigned w) { return __uint_as_float(w << 16); }
; __device__ __forceinline__ float bf_hi(unsigned w) { return __uint_as_float(w & 0xffff0000u); }
; __device__ __forceinline__ float softplus_(float x) { return fmaxf(x, 0.f) + __logf(1.0f + __expf(-fabsf(x))); }
; #define LBAR() do { asm volatile("s_waitcnt lgkmcnt(0)" ::: "memory"); __builtin_amdgcn_s_barrier(); asm volatile("" ::: "memory"); } while (0)
; __device__ void gla_chunk_phase(const Params& p, int l, LAS unsigned char* lds) {
;     ...
;             LBAR();
; #pragma unroll
;             for (int i = 0; i < 2; ++i) { const int id = wid + 8 * i, rt = id >> 2, ct = id & 3; const f32x4 z4 = {0.f, 0.f, 0.f, 0.f};
;                 const f32x4 z = mm_nt<1>(dnA, 40, rt * 16, upT, 40, ct * 16, r16, quad, z4);
;                 const int col = ct * 16 + r16; const float bz = bias_s[col];
;                 f32x4 la, lo;
; #pragma unroll
;                 for (int j = 0; j < 4; ++j) la[j] = -softplus_(-(z[j] + bz)) * (1.0f / 16.0f);
;                 const unsigned h01 = cvt_pk_bf16(la[0], la[1]), h23 = cvt_pk_bf16(la[2], la[3]);
;                 lo[0] = la[0] - bf_lo(h01); lo[1] = la[1] - bf_hi(h01); lo[2] = la[2] - bf_lo(h23); lo[3] = la[3] - bf_hi(h23);
;                 u32x2 hw; hw.x = h01; hw.y = h23; *(LAS u32x2*)(laT_hi + col * 72 + rt * 16 + quad * 4) = hw;
;                 st_bf4(laT_lo + col * 72 + rt * 16 + quad * 4, lo); }
;             LBAR();
; #pragma unroll
;             for (int i = 0; i < 2; ++i) { const int id = wid + 8 * i, rt = id >> 2, ct = id & 3; const f32x4 z4 = {0.f, 0.f, 0.f, 0.f};
;                 f32x4 acc = mm_nt<2>(Lm, 72, rt * 16, laT_hi, 72, ct * 16, r16, quad, z4);
;                 acc = mm_nt<2>(Lm, 72, rt * 16, laT_lo, 72, ct * 16, r16, quad, acc);
;                 const int col = ct * 16 + r16;
; #pragma unroll
;                 for (int j = 0; j < 4; ++j) b_s[(rt * 16 + quad * 4 + j) * 64 + col] = acc[j];
;                 if (rt == 3 && quad == 3) { tot_s[col] = acc[3]; dk_s[col] = __expf(acc[3]); } }
.LBB0_443:
	s_cmp_eq_u32 s100, 0
	s_cbranch_scc1 .Lgla_noG1
	s_waitcnt lgkmcnt(0)
	s_barrier
.Lgla_noG1:
	v_add_u32_e32 v42, v69, v83
	ds_read_b128 v[42:45], v42
	ds_read_b128 v[116:119], v70
	ds_read_b32 v53, v71
	ds_read_b128 v[204:207], v105
	s_waitcnt lgkmcnt(0)
	v_mfma_f32_16x16x32_bf16 v[42:45], v[42:45], v[116:119], 0
	v_mfma_f32_16x16x32_bf16 v[204:207], v[204:207], v[116:119], 0
	v_mov_b32_e32 v208, v53
	s_nop 7
	v_add_f32_e32 v62, v53, v42
	v_max_f32_e64 v42, -v62, 0
	v_mul_f32_e64 v62, |v62|, s97
	v_exp_f32_e32 v62, v62
	s_nop 0
	v_add_f32_e32 v62, 1.0, v62
	v_log_f32_e32 v62, v62
	s_nop 0
	v_mul_f32_e32 v63, 0x3f317217, v62
	v_fma_f32 v63, v62, s48, -v63
	v_fmac_f32_e32 v63, 0x3377d1cf, v62
	v_fmac_f32_e32 v63, 0x3f317217, v62
	v_mov_b32_e32 v62, v63
	v_add_f32_e32 v63, v53, v43
	v_max_f32_e64 v43, -v63, 0
	v_mul_f32_e64 v63, |v63|, s97
	v_exp_f32_e32 v63, v63
	s_nop 0
	v_add_f32_e32 v63, 1.0, v63
	v_log_f32_e32 v63, v63
	s_nop 0
	v_mul_f32_e32 v115, 0x3f317217, v63
	v_fma_f32 v115, v63, s48, -v115
	v_fmac_f32_e32 v115, 0x3377d1cf, v63
	v_fmac_f32_e32 v115, 0x3f317217, v63
	v_mov_b32_e32 v63, v115
	v_add_f32_e32 v115, v53, v44
	v_max_f32_e64 v44, -v115, 0
	v_mul_f32_e64 v115, |v115|, s97
	v_exp_f32_e32 v115, v115
	v_add_f32_e32 v53, v53, v45
	v_max_f32_e64 v45, -v53, 0
	v_mul_f32_e64 v53, |v53|, s97
	v_add_f32_e32 v115, 1.0, v115
	v_exp_f32_e32 v53, v53
	v_pk_add_f32 v[42:43], v[42:43], v[62:63]
	v_log_f32_e32 v115, v115
	v_add_f32_e32 v53, 1.0, v53
	v_pk_mul_f32 v[62:63], v[42:43], s[96:97] op_sel_hi:[1,0]
	v_mul_f32_e32 v116, 0x3f317217, v115
	v_fma_f32 v116, v115, s48, -v116
	v_fmac_f32_e32 v116, 0x3377d1cf, v115
	v_fmac_f32_e32 v116, 0x3f317217, v115
	v_cvt_pk_bf16_f32 v62, v62, v63
	v_lshlrev_b32_e32 v118, 16, v62
	v_mov_b32_e32 v115, v116
	v_mov_b32_e32 v116, v115
	v_and_b32_e32 v119, 0xffff0000, v62
	v_log_f32_e32 v53, v53
	v_pk_fma_f32 v[42:43], v[42:43], s[96:97], v[118:119] op_sel_hi:[1,0,1] neg_lo:[0,0,1] neg_hi:[0,0,1]
	v_mul_f32_e32 v115, 0x3f317217, v53
	v_fma_f32 v115, v53, s48, -v115
	v_fmac_f32_e32 v115, 0x3377d1cf, v53
	v_fmac_f32_e32 v115, 0x3f317217, v53
	v_cvt_pk_bf16_f32 v42, v42, v43
	s_nop 0
	v_mov_b32_e32 v53, v115
	v_mov_b32_e32 v117, v53
	v_pk_add_f32 v[44:45], v[44:45], v[116:117]
	s_nop 0
	v_pk_mul_f32 v[116:117], v[44:45], s[96:97] op_sel_hi:[1,0]
	s_nop 0
	v_cvt_pk_bf16_f32 v63, v116, v117
	v_lshlrev_b32_e32 v116, 16, v63
	v_and_b32_e32 v117, 0xffff0000, v63
	v_pk_fma_f32 v[44:45], v[44:45], s[96:97], v[116:117] op_sel_hi:[1,0,1] neg_lo:[0,0,1] neg_hi:[0,0,1]
	ds_write_b64 v84, v[62:63]
	v_cvt_pk_bf16_f32 v43, v44, v45
	ds_write_b64 v85, v[42:43]
	v_mov_b64_e32 v[42:43], v[204:205]
	v_mov_b64_e32 v[44:45], v[206:207]
	v_mov_b32_e32 v53, v208
	v_add_f32_e32 v62, v53, v42
	v_max_f32_e64 v42, -v62, 0
	v_mul_f32_e64 v62, |v62|, s97
	v_exp_f32_e32 v62, v62
	s_nop 0
	v_add_f32_e32 v62, 1.0, v62
	v_log_f32_e32 v62, v62
	s_nop 0
	v_mul_f32_e32 v63, 0x3f317217, v62
	v_fma_f32 v63, v62, s48, -v63
	v_fmac_f32_e32 v63, 0x3377d1cf, v62
	v_fmac_f32_e32 v63, 0x3f317217, v62
	v_mov_b32_e32 v62, v63
	v_add_f32_e32 v63, v53, v43
	v_max_f32_e64 v43, -v63, 0
	v_mul_f32_e64 v63, |v63|, s97
	v_exp_f32_e32 v63, v63
	s_nop 0
	v_add_f32_e32 v63, 1.0, v63
	v_log_f32_e32 v63, v63
	s_nop 0
	v_mul_f32_e32 v115, 0x3f317217, v63
	v_fma_f32 v115, v63, s48, -v115
	v_fmac_f32_e32 v115, 0x3377d1cf, v63
	v_fmac_f32_e32 v115, 0x3f317217, v63
	v_mov_b32_e32 v63, v115
	v_add_f32_e32 v115, v53, v44
	v_max_f32_e64 v44, -v115, 0
	v_mul_f32_e64 v115, |v115|, s97
	v_exp_f32_e32 v115, v115
	v_add_f32_e32 v53, v53, v45
	v_max_f32_e64 v45, -v53, 0
	v_mul_f32_e64 v53, |v53|, s97
	v_add_f32_e32 v115, 1.0, v115
	v_exp_f32_e32 v53, v53
	v_pk_add_f32 v[42:43], v[42:43], v[62:63]
	v_log_f32_e32 v115, v115
	v_add_f32_e32 v53, 1.0, v53
	v_pk_mul_f32 v[62:63], v[42:43], s[96:97] op_sel_hi:[1,0]
	v_mul_f32_e32 v116, 0x3f317217, v115
	v_fma_f32 v116, v115, s48, -v116
	v_fmac_f32_e32 v116, 0x3377d1cf, v115
	v_fmac_f32_e32 v116, 0x3f317217, v115
	v_cvt_pk_bf16_f32 v62, v62, v63
	v_lshlrev_b32_e32 v118, 16, v62
	v_mov_b32_e32 v115, v116
	v_mov_b32_e32 v116, v115
	v_and_b32_e32 v119, 0xffff0000, v62
	v_log_f32_e32 v53, v53
	v_pk_fma_f32 v[42:43], v[42:43], s[96:97], v[118:119] op_sel_hi:[1,0,1] neg_lo:[0,0,1] neg_hi:[0,0,1]
	v_mul_f32_e32 v115, 0x3f317217, v53
	v_fma_f32 v115, v53, s48, -v115
	v_fmac_f32_e32 v115, 0x3377d1cf, v53
	v_fmac_f32_e32 v115, 0x3f317217, v53
	v_cvt_pk_bf16_f32 v42, v42, v43
	s_nop 0
	v_mov_b32_e32 v53, v115
	v_mov_b32_e32 v117, v53
	v_pk_add_f32 v[44:45], v[44:45], v[116:117]
	v_add_u32_e32 v53, v72, v68
	v_pk_mul_f32 v[116:117], v[44:45], s[96:97] op_sel_hi:[1,0]
	s_nop 0
	v_cvt_pk_bf16_f32 v63, v116, v117
	v_lshlrev_b32_e32 v116, 16, v63
	v_and_b32_e32 v117, 0xffff0000, v63
	v_pk_fma_f32 v[44:45], v[44:45], s[96:97], v[116:117] op_sel_hi:[1,0,1] neg_lo:[0,0,1] neg_hi:[0,0,1]
	ds_write_b64 v84, v[62:63] offset:64
	v_cvt_pk_bf16_f32 v43, v44, v45
	ds_write_b64 v85, v[42:43] offset:64
	s_waitcnt lgkmcnt(0)
	s_barrier
	ds_read_b128 v[42:45], v106
	ds_read_b128 v[120:123], v106 offset:64
	ds_read_b128 v[180:183], v108
	ds_read_b128 v[184:187], v108 offset:64
	ds_read_b128 v[116:119], v53
	ds_read_b128 v[124:127], v53 offset:64
	v_add_u32_e32 v62, v73, v68
	ds_read_b128 v[188:191], v62
	ds_read_b128 v[192:195], v62 offset:64
	s_waitcnt lgkmcnt(0)
	v_mfma_f32_16x16x32_bf16 v[196:199], v[42:45], v[116:119], 0
	v_mfma_f32_16x16x32_bf16 v[200:203], v[180:183], v[116:119], 0
	v_mfma_f32_16x16x32_bf16 v[196:199], v[120:123], v[124:127], v[196:199]
	v_mfma_f32_16x16x32_bf16 v[200:203], v[184:187], v[124:127], v[200:203]
	v_mfma_f32_16x16x32_bf16 v[196:199], v[42:45], v[188:191], v[196:199]
	v_mfma_f32_16x16x32_bf16 v[200:203], v[180:183], v[188:191], v[200:203]
	v_mfma_f32_16x16x32_bf16 v[196:199], v[120:123], v[192:195], v[196:199]
	v_mfma_f32_16x16x32_bf16 v[200:203], v[184:187], v[192:195], v[200:203]
	s_nop 6
	ds_write2st64_b32 v107, v196, v197 offset1:1
	ds_write2st64_b32 v107, v198, v199 offset0:2 offset1:3
	s_and_saveexec_b64 s[20:21], s[88:89]
	s_cbranch_execz .LBB0_445
	v_mul_f32_e32 v42, 0x3fb8aa3b, v199
	v_exp_f32_e32 v42, v42
	ds_write_b32 v75, v199
	ds_write_b32 v74, v42

; __global__ void __launch_bounds__(512, 2) fwd_kernel(Params p, int ph_lo, int ph_hi) {
	.amdhsa_kernel _Z10fwd_kernel6Paramsii
		.amdhsa_group_segment_fixed_size 0
		.amdhsa_private_segment_fixed_size 0
		.amdhsa_kernarg_size 568
		.amdhsa_user_sgpr_count 2
		.amdhsa_user_sgpr_dispatch_ptr 0
		.amdhsa_user_sgpr_queue_ptr 0
		.amdhsa_user_sgpr_kernarg_segment_ptr 1
		.amdhsa_user_sgpr_dispatch_id 0
		.amdhsa_user_sgpr_kernarg_preload_length 0
		.amdhsa_user_sgpr_kernarg_preload_offset 0
		.amdhsa_user_sgpr_private_segment_size 0
		.amdhsa_uses_dynamic_stack 0
		.amdhsa_enable_private_segment 0
		.amdhsa_system_sgpr_workgroup_id_x 1
		.amdhsa_system_sgpr_workgroup_id_y 0
		.amdhsa_system_sgpr_workgroup_id_z 0
		.amdhsa_system_sgpr_workgroup_info 0
		.amdhsa_system_vgpr_workitem_id 2
		.amdhsa_next_free_vgpr 256
		.amdhsa_next_free_sgpr 102
		.amdhsa_accum_offset 256
		.amdhsa_reserve_vcc 1
		.amdhsa_float_round_mode_32 0
		.amdhsa_float_round_mode_16_64 0
		.amdhsa_float_denorm_mode_32 3
		.amdhsa_float_denorm_mode_16_64 3
		.amdhsa_dx10_clamp 1
		.amdhsa_ieee_mode 1
		.amdhsa_fp16_overflow 0
		.amdhsa_tg_split 0
		.amdhsa_exception_fp_ieee_invalid_op 0
		.amdhsa_exception_fp_denorm_src 0
		.amdhsa_exception_fp_ieee_div_zero 0
		.amdhsa_exception_fp_ieee_overflow 0
		.amdhsa_exception_fp_ieee_underflow 0
		.amdhsa_exception_fp_ieee_inexact 0
		.amdhsa_exception_int_div_zero 0
	.end_amdhsa_kernel

; __global__ void __launch_bounds__(512, 2) fwd_kernel(Params p, int ph_lo, int ph_hi) {
amdhsa.kernels:
  - .agpr_count:     0
    .args:
      - .offset:         0
        .size:           304
        .value_kind:     by_value
      - .offset:         304
        .size:           4
        .value_kind:     by_value
      - .offset:         308
        .size:           4
        .value_kind:     by_value
      - .offset:         312
        .size:           4
        .value_kind:     hidden_block_count_x
      - .offset:         316
        .size:           4
        .value_kind:     hidden_block_count_y
      - .offset:         320
        .size:           4
        .value_kind:     hidden_block_count_z
      - .offset:         324
        .size:           2
        .value_kind:     hidden_group_size_x
      - .offset:         326
        .size:           2
        .value_kind:     hidden_group_size_y
      - .offset:         328
        .size:           2
        .value_kind:     hidden_group_size_z
      - .offset:         330
        .size:           2
        .value_kind:     hidden_remainder_x
      - .offset:         332
        .size:           2
        .value_kind:     hidden_remainder_y
      - .offset:         334
        .size:           2
        .value_kind:     hidden_remainder_z
      - .offset:         352
        .size:           8
        .value_kind:     hidden_global_offset_x
      - .offset:         360
        .size:           8
        .value_kind:     hidden_global_offset_y
      - .offset:         368
        .size:           8
        .value_kind:     hidden_global_offset_z
      - .offset:         376
        .size:           2
        .value_kind:     hidden_grid_dims
      - .offset:         400
        .size:           8
        .value_kind:     hidden_multigrid_sync_arg
      - .offset:         432
        .size:           4
        .value_kind:     hidden_dynamic_lds_size
    .group_segment_fixed_size: 0
    .kernarg_segment_align: 8
    .kernarg_segment_size: 568
    .language:       OpenCL C
    .language_version:
      - 2
      - 0
    .max_flat_workgroup_size: 512
    .name:           _Z10fwd_kernel6Paramsii
    .private_segment_fixed_size: 0
    .sgpr_count:     108
    .sgpr_spill_count: 169
    .symbol:         _Z10fwd_kernel6Paramsii.kd
    .uniform_work_group_size: 1
    .uses_dynamic_stack: false
    .vgpr_count:     256
    .vgpr_spill_count: 0
    .wavefront_size: 64
